# P7 K loop: LDS-DMA tile loads in SGPR-base form (32-bit lane offset) instead of 64-bit VALU address adds (13 of 16 per body)
# baseline (speedup 1.0000x reference)
.LBB0_1034:
	ds_read_b128 v[146:149], v156
	ds_read_b128 v[150:153], v156 offset:1024
	ds_read_b128 v[162:165], v156 offset:2048
	ds_read_b128 v[166:169], v156 offset:3072
	ds_read_b128 v[170:173], v157
	ds_read_b128 v[174:177], v157 offset:1024
	ds_read_b128 v[178:181], v157 offset:2048
	ds_read_b128 v[182:185], v157 offset:3072
	s_add_u32 s42, s40, 0xfffc0080
	s_addc_u32 s43, s41, -1
	s_cmp_eq_u32 s63, 12
	s_cselect_b32 s45, s29, s43
	s_cselect_b32 s44, s59, s42
	s_cselect_b32 s43, s27, s62
	s_cselect_b32 s42, s60, s61
	s_add_i32 m0, s48, 0xc000
	ds_read_b128 v[186:189], v158
	ds_read_b128 v[190:193], v158 offset:1024
	ds_read_b128 v[194:197], v158 offset:2048
	ds_read_b128 v[200:203], v158 offset:3072
	ds_read_b128 v[204:207], v158 offset:4096
	ds_read_b128 v[208:211], v158 offset:5120
	ds_read_b128 v[212:215], v158 offset:6144
	ds_read_b128 v[216:219], v158 offset:7168
	global_load_lds_dwordx4 v138, s[40:41]
	s_add_i32 m0, s48, 0xe000
	s_nop 0
	global_load_lds_dwordx4 v140, s[40:41]
	s_waitcnt vmcnt(8)
	s_waitcnt lgkmcnt(0)
	s_barrier
	s_setprio 1
	s_waitcnt lgkmcnt(0)
	v_mfma_f32_16x16x32_bf16 v[126:129], v[146:149], v[186:189], v[126:129]
	v_mfma_f32_16x16x32_bf16 v[122:125], v[162:165], v[186:189], v[122:125]
	v_mfma_f32_16x16x32_bf16 v[110:113], v[146:149], v[194:197], v[110:113]
	v_mfma_f32_16x16x32_bf16 v[106:109], v[162:165], v[194:197], v[106:109]
	v_mfma_f32_16x16x32_bf16 v[94:97], v[146:149], v[204:207], v[94:97]
	v_mfma_f32_16x16x32_bf16 v[90:93], v[162:165], v[204:207], v[90:93]
	v_mfma_f32_16x16x32_bf16 v[78:81], v[146:149], v[212:215], v[78:81]
	v_mfma_f32_16x16x32_bf16 v[74:77], v[162:165], v[212:215], v[74:77]
	v_mfma_f32_16x16x32_bf16 v[126:129], v[150:153], v[190:193], v[126:129]
	v_mfma_f32_16x16x32_bf16 v[122:125], v[166:169], v[190:193], v[122:125]
	v_mfma_f32_16x16x32_bf16 v[110:113], v[150:153], v[200:203], v[110:113]
	v_mfma_f32_16x16x32_bf16 v[106:109], v[166:169], v[200:203], v[106:109]
	v_mfma_f32_16x16x32_bf16 v[94:97], v[150:153], v[208:211], v[94:97]
	v_mfma_f32_16x16x32_bf16 v[90:93], v[166:169], v[208:211], v[90:93]
	v_mfma_f32_16x16x32_bf16 v[78:81], v[150:153], v[216:219], v[78:81]
	v_mfma_f32_16x16x32_bf16 v[74:77], v[166:169], v[216:219], v[74:77]
	s_setprio 0
	s_setprio 1
	v_mfma_f32_16x16x32_bf16 v[118:121], v[170:173], v[186:189], v[118:121]
	v_mfma_f32_16x16x32_bf16 v[114:117], v[178:181], v[186:189], v[114:117]
	v_mfma_f32_16x16x32_bf16 v[102:105], v[170:173], v[194:197], v[102:105]
	v_mfma_f32_16x16x32_bf16 v[98:101], v[178:181], v[194:197], v[98:101]
	v_mfma_f32_16x16x32_bf16 v[86:89], v[170:173], v[204:207], v[86:89]
	v_mfma_f32_16x16x32_bf16 v[82:85], v[178:181], v[204:207], v[82:85]
	v_mfma_f32_16x16x32_bf16 v[70:73], v[170:173], v[212:215], v[70:73]
	v_mfma_f32_16x16x32_bf16 v[66:69], v[178:181], v[212:215], v[66:69]
	v_mfma_f32_16x16x32_bf16 v[118:121], v[174:177], v[190:193], v[118:121]
	v_mfma_f32_16x16x32_bf16 v[114:117], v[182:185], v[190:193], v[114:117]
	v_mfma_f32_16x16x32_bf16 v[102:105], v[174:177], v[200:203], v[102:105]
	v_mfma_f32_16x16x32_bf16 v[98:101], v[182:185], v[200:203], v[98:101]
	v_mfma_f32_16x16x32_bf16 v[86:89], v[174:177], v[208:211], v[86:89]
	v_mfma_f32_16x16x32_bf16 v[82:85], v[182:185], v[208:211], v[82:85]
	v_mfma_f32_16x16x32_bf16 v[70:73], v[174:177], v[216:219], v[70:73]
	v_mfma_f32_16x16x32_bf16 v[66:69], v[182:185], v[216:219], v[66:69]
	s_setprio 0
	s_barrier
	s_add_i32 s64, s55, s46
	s_mov_b32 m0, s64
	ds_read_b128 v[186:189], v158 offset:16384
	ds_read_b128 v[190:193], v158 offset:17408
	ds_read_b128 v[194:197], v158 offset:18432
	ds_read_b128 v[200:203], v158 offset:19456
	ds_read_b128 v[204:207], v158 offset:20480
	ds_read_b128 v[208:211], v158 offset:21504
	ds_read_b128 v[212:215], v158 offset:22528
	ds_read_b128 v[216:219], v158 offset:23552
	global_load_lds_dwordx4 v134, s[42:43]
	s_add_i32 m0, s64, 0x2000
	s_add_u32 s64, s42, 0x40000
	v_lshl_add_u64 v[222:223], s[42:43], 0, v[130:131]
	s_addc_u32 s65, s43, 0
	s_add_i32 s66, s56, s46
	global_load_lds_dwordx4 v130, s[42:43]
	s_mov_b32 m0, s66
	v_lshl_add_u64 v[226:227], s[44:45], 0, v[132:133]
	global_load_lds_dwordx4 v134, s[64:65]
	s_add_i32 m0, s66, 0x2000
	s_nop 0
	global_load_lds_dwordx4 v130, s[64:65]
	v_lshl_add_u64 v[224:225], s[44:45], 0, v[136:137]
	s_mov_b32 m0, s48
	s_nop 0
	global_load_lds_dwordx4 v136, s[44:45]
	s_mov_b32 m0, s49
	s_nop 0
	global_load_lds_dwordx4 v132, s[44:45]
	s_waitcnt vmcnt(8)
	s_waitcnt lgkmcnt(0)
	s_barrier
	s_setprio 1
	s_waitcnt lgkmcnt(0)
	v_mfma_f32_16x16x32_bf16 v[62:65], v[146:149], v[186:189], v[62:65]
	v_mfma_f32_16x16x32_bf16 v[58:61], v[162:165], v[186:189], v[58:61]
	v_mfma_f32_16x16x32_bf16 v[46:49], v[146:149], v[194:197], v[46:49]
	v_mfma_f32_16x16x32_bf16 v[42:45], v[162:165], v[194:197], v[42:45]
	v_mfma_f32_16x16x32_bf16 v[30:33], v[146:149], v[204:207], v[30:33]
	v_mfma_f32_16x16x32_bf16 v[26:29], v[162:165], v[204:207], v[26:29]
	v_mfma_f32_16x16x32_bf16 v[14:17], v[146:149], v[212:215], v[14:17]
	v_mfma_f32_16x16x32_bf16 v[10:13], v[162:165], v[212:215], v[10:13]
	v_mfma_f32_16x16x32_bf16 v[62:65], v[150:153], v[190:193], v[62:65]
	v_mfma_f32_16x16x32_bf16 v[58:61], v[166:169], v[190:193], v[58:61]
	v_mfma_f32_16x16x32_bf16 v[46:49], v[150:153], v[200:203], v[46:49]
	v_mfma_f32_16x16x32_bf16 v[42:45], v[166:169], v[200:203], v[42:45]
	v_mfma_f32_16x16x32_bf16 v[30:33], v[150:153], v[208:211], v[30:33]
	v_mfma_f32_16x16x32_bf16 v[26:29], v[166:169], v[208:211], v[26:29]
	v_mfma_f32_16x16x32_bf16 v[14:17], v[150:153], v[216:219], v[14:17]
	v_mfma_f32_16x16x32_bf16 v[10:13], v[166:169], v[216:219], v[10:13]
	s_setprio 0
	s_setprio 1
	v_mfma_f32_16x16x32_bf16 v[54:57], v[170:173], v[186:189], v[54:57]
	v_mfma_f32_16x16x32_bf16 v[50:53], v[178:181], v[186:189], v[50:53]
	v_mfma_f32_16x16x32_bf16 v[38:41], v[170:173], v[194:197], v[38:41]
	v_mfma_f32_16x16x32_bf16 v[34:37], v[178:181], v[194:197], v[34:37]
	v_mfma_f32_16x16x32_bf16 v[22:25], v[170:173], v[204:207], v[22:25]
	v_mfma_f32_16x16x32_bf16 v[18:21], v[178:181], v[204:207], v[18:21]
	v_mfma_f32_16x16x32_bf16 v[6:9], v[170:173], v[212:215], v[6:9]
	v_mfma_f32_16x16x32_bf16 v[2:5], v[178:181], v[212:215], v[2:5]
	v_mfma_f32_16x16x32_bf16 v[54:57], v[174:177], v[190:193], v[54:57]
	v_mfma_f32_16x16x32_bf16 v[50:53], v[182:185], v[190:193], v[50:53]
	v_mfma_f32_16x16x32_bf16 v[38:41], v[174:177], v[200:203], v[38:41]
	v_mfma_f32_16x16x32_bf16 v[34:37], v[182:185], v[200:203], v[34:37]
	v_mfma_f32_16x16x32_bf16 v[22:25], v[174:177], v[208:211], v[22:25]
	v_mfma_f32_16x16x32_bf16 v[18:21], v[182:185], v[208:211], v[18:21]
	v_mfma_f32_16x16x32_bf16 v[6:9], v[174:177], v[216:219], v[6:9]
	v_mfma_f32_16x16x32_bf16 v[2:5], v[182:185], v[216:219], v[2:5]
	s_setprio 0
	s_barrier
	s_add_i32 s64, 0, 0x18000
	v_add_u32_e32 v161, s64, v154
	s_add_i32 s65, 0, 0x1c000
	ds_read_b128 v[146:149], v161
	ds_read_b128 v[150:153], v161 offset:1024
	ds_read_b128 v[162:165], v161 offset:2048
	ds_read_b128 v[166:169], v161 offset:3072
	v_add_u32_e32 v161, s65, v154
	ds_read_b128 v[170:173], v161
	ds_read_b128 v[174:177], v161 offset:1024
	ds_read_b128 v[178:181], v161 offset:2048
	ds_read_b128 v[182:185], v161 offset:3072
	s_add_u32 s44, s44, 0x40000
	s_addc_u32 s45, s45, 0
	s_mov_b32 m0, s50
	ds_read_b128 v[186:189], v158 offset:32768
	ds_read_b128 v[190:193], v158 offset:33792
	ds_read_b128 v[194:197], v158 offset:34816
	ds_read_b128 v[200:203], v158 offset:35840
	ds_read_b128 v[204:207], v158 offset:36864
	ds_read_b128 v[208:211], v158 offset:37888
	ds_read_b128 v[212:215], v158 offset:38912
	ds_read_b128 v[216:219], v158 offset:39936
	global_load_lds_dwordx4 v136, s[44:45]
	s_mov_b32 m0, s51
	s_nop 0
	global_load_lds_dwordx4 v132, s[44:45]
	s_waitcnt vmcnt(8)
	s_waitcnt lgkmcnt(0)
	s_barrier
	s_setprio 1
	s_waitcnt lgkmcnt(0)
	v_mfma_f32_16x16x32_bf16 v[126:129], v[146:149], v[186:189], v[126:129]
	v_mfma_f32_16x16x32_bf16 v[122:125], v[162:165], v[186:189], v[122:125]
	v_mfma_f32_16x16x32_bf16 v[110:113], v[146:149], v[194:197], v[110:113]
	v_mfma_f32_16x16x32_bf16 v[106:109], v[162:165], v[194:197], v[106:109]
	v_mfma_f32_16x16x32_bf16 v[94:97], v[146:149], v[204:207], v[94:97]
	v_mfma_f32_16x16x32_bf16 v[90:93], v[162:165], v[204:207], v[90:93]
	v_mfma_f32_16x16x32_bf16 v[78:81], v[146:149], v[212:215], v[78:81]
	v_mfma_f32_16x16x32_bf16 v[74:77], v[162:165], v[212:215], v[74:77]
	v_mfma_f32_16x16x32_bf16 v[126:129], v[150:153], v[190:193], v[126:129]
	v_mfma_f32_16x16x32_bf16 v[122:125], v[166:169], v[190:193], v[122:125]
	v_mfma_f32_16x16x32_bf16 v[110:113], v[150:153], v[200:203], v[110:113]
	v_mfma_f32_16x16x32_bf16 v[106:109], v[166:169], v[200:203], v[106:109]
	v_mfma_f32_16x16x32_bf16 v[94:97], v[150:153], v[208:211], v[94:97]
	v_mfma_f32_16x16x32_bf16 v[90:93], v[166:169], v[208:211], v[90:93]
	v_mfma_f32_16x16x32_bf16 v[78:81], v[150:153], v[216:219], v[78:81]
	v_mfma_f32_16x16x32_bf16 v[74:77], v[166:169], v[216:219], v[74:77]
	s_setprio 0
	s_setprio 1
	v_mfma_f32_16x16x32_bf16 v[118:121], v[170:173], v[186:189], v[118:121]
	v_mfma_f32_16x16x32_bf16 v[114:117], v[178:181], v[186:189], v[114:117]
	v_mfma_f32_16x16x32_bf16 v[102:105], v[170:173], v[194:197], v[102:105]
	v_mfma_f32_16x16x32_bf16 v[98:101], v[178:181], v[194:197], v[98:101]
	v_mfma_f32_16x16x32_bf16 v[86:89], v[170:173], v[204:207], v[86:89]
	v_mfma_f32_16x16x32_bf16 v[82:85], v[178:181], v[204:207], v[82:85]
	v_mfma_f32_16x16x32_bf16 v[70:73], v[170:173], v[212:215], v[70:73]
	v_mfma_f32_16x16x32_bf16 v[66:69], v[178:181], v[212:215], v[66:69]
	v_mfma_f32_16x16x32_bf16 v[118:121], v[174:177], v[190:193], v[118:121]
	v_mfma_f32_16x16x32_bf16 v[114:117], v[182:185], v[190:193], v[114:117]
	v_mfma_f32_16x16x32_bf16 v[102:105], v[174:177], v[200:203], v[102:105]
	v_mfma_f32_16x16x32_bf16 v[98:101], v[182:185], v[200:203], v[98:101]
	v_mfma_f32_16x16x32_bf16 v[86:89], v[174:177], v[208:211], v[86:89]
	v_mfma_f32_16x16x32_bf16 v[82:85], v[182:185], v[208:211], v[82:85]
	v_mfma_f32_16x16x32_bf16 v[70:73], v[174:177], v[216:219], v[70:73]
	v_mfma_f32_16x16x32_bf16 v[66:69], v[182:185], v[216:219], v[66:69]
	s_setprio 0
	s_barrier
; template <class Epi, bool HOOK = false>
; DI void gemm_phase(LAS unsigned char* lds, const Gemm g, const StaticOrder& S, const Epi& E) {
;     ...
;         if constexpr (HOOK) {
;             for (int t = 0; t < (nt >> 1); t += 2) PG8_KBODY();
;             E.hook(acc, cur, wr, wc, fr, fq);
;             for (int t = (nt >> 1); t < nt; t += 2) PG8_KBODY();
;         } else {
;             for (int t = 0; t < nt; t += 2) PG8_KBODY();
;     DI void operator()(const Acc& acc, const Unit& u, int wr, int wc, int fr, int fq) const {
;         const int row0 = u.pm * 256 + wr * 64 + fr;
; #pragma unroll
;         for (int ai = 0; ai < 2; ++ai)
; #pragma unroll
;             for (int m = 0; m < 4; ++m) {
;                 const int r = row0 + ai * 128 + m * 16;
;                 const f32x4* sp = (const f32x4*)(SS + (size_t)r * 16);
;                 const f32x4 s0 = sp[0], s1 = sp[1], s2 = sp[2], s3 = sp[3];
	s_add_i32 s44, s64, s46
	v_add_u32_e32 v220, 0x80, v134
	s_mov_b32 m0, s44
	ds_read_b128 v[186:189], v158 offset:49152
	ds_read_b128 v[190:193], v158 offset:50176
	ds_read_b128 v[194:197], v158 offset:51200
	ds_read_b128 v[200:203], v158 offset:52224
	ds_read_b128 v[204:207], v158 offset:53248
	ds_read_b128 v[208:211], v158 offset:54272
	ds_read_b128 v[212:215], v158 offset:55296
	ds_read_b128 v[216:219], v158 offset:56320
	global_load_lds_dwordx4 v220, s[42:43]
	s_add_i32 m0, s44, 0x2000
	s_add_u32 s42, s42, 0x40080
	v_lshl_add_u64 v[220:221], v[222:223], 0, s[16:17]
	s_addc_u32 s43, s43, 0
	s_add_i32 s44, s65, s46
	global_load_lds_dwordx4 v[220:221], off
	s_mov_b32 m0, s44
	s_nop 0
	global_load_lds_dwordx4 v134, s[42:43]
	s_add_i32 m0, s44, 0x2000
	s_nop 0
	global_load_lds_dwordx4 v130, s[42:43]
	v_lshl_add_u64 v[220:221], v[224:225], 0, s[16:17]
	s_mov_b32 m0, s53
	s_nop 0
	global_load_lds_dwordx4 v[220:221], off
	v_lshl_add_u64 v[220:221], v[226:227], 0, s[16:17]
	s_mov_b32 m0, s54
	s_nop 0
	global_load_lds_dwordx4 v[220:221], off
	s_waitcnt vmcnt(8)
	s_waitcnt lgkmcnt(0)
	s_barrier
	s_setprio 1
	s_waitcnt lgkmcnt(0)
	v_mfma_f32_16x16x32_bf16 v[62:65], v[146:149], v[186:189], v[62:65]
	v_mfma_f32_16x16x32_bf16 v[58:61], v[162:165], v[186:189], v[58:61]
	v_mfma_f32_16x16x32_bf16 v[46:49], v[146:149], v[194:197], v[46:49]
	v_mfma_f32_16x16x32_bf16 v[42:45], v[162:165], v[194:197], v[42:45]
	v_mfma_f32_16x16x32_bf16 v[30:33], v[146:149], v[204:207], v[30:33]
	v_mfma_f32_16x16x32_bf16 v[26:29], v[162:165], v[204:207], v[26:29]
	v_mfma_f32_16x16x32_bf16 v[14:17], v[146:149], v[212:215], v[14:17]
	v_mfma_f32_16x16x32_bf16 v[10:13], v[162:165], v[212:215], v[10:13]
	v_mfma_f32_16x16x32_bf16 v[62:65], v[150:153], v[190:193], v[62:65]
	v_mfma_f32_16x16x32_bf16 v[58:61], v[166:169], v[190:193], v[58:61]
	v_mfma_f32_16x16x32_bf16 v[46:49], v[150:153], v[200:203], v[46:49]
	v_mfma_f32_16x16x32_bf16 v[42:45], v[166:169], v[200:203], v[42:45]
	v_mfma_f32_16x16x32_bf16 v[30:33], v[150:153], v[208:211], v[30:33]
	v_mfma_f32_16x16x32_bf16 v[26:29], v[166:169], v[208:211], v[26:29]
	v_mfma_f32_16x16x32_bf16 v[14:17], v[150:153], v[216:219], v[14:17]
	v_mfma_f32_16x16x32_bf16 v[10:13], v[166:169], v[216:219], v[10:13]
	s_setprio 0
	s_setprio 1
	v_mfma_f32_16x16x32_bf16 v[54:57], v[170:173], v[186:189], v[54:57]
	v_mfma_f32_16x16x32_bf16 v[50:53], v[178:181], v[186:189], v[50:53]
	v_mfma_f32_16x16x32_bf16 v[38:41], v[170:173], v[194:197], v[38:41]
	v_mfma_f32_16x16x32_bf16 v[34:37], v[178:181], v[194:197], v[34:37]
	v_mfma_f32_16x16x32_bf16 v[22:25], v[170:173], v[204:207], v[22:25]
	v_mfma_f32_16x16x32_bf16 v[18:21], v[178:181], v[204:207], v[18:21]
	v_mfma_f32_16x16x32_bf16 v[6:9], v[170:173], v[212:215], v[6:9]
	v_mfma_f32_16x16x32_bf16 v[2:5], v[178:181], v[212:215], v[2:5]
	v_mfma_f32_16x16x32_bf16 v[54:57], v[174:177], v[190:193], v[54:57]
	v_mfma_f32_16x16x32_bf16 v[50:53], v[182:185], v[190:193], v[50:53]
	v_mfma_f32_16x16x32_bf16 v[38:41], v[174:177], v[200:203], v[38:41]
	v_mfma_f32_16x16x32_bf16 v[34:37], v[182:185], v[200:203], v[34:37]
	v_mfma_f32_16x16x32_bf16 v[22:25], v[174:177], v[208:211], v[22:25]
	v_mfma_f32_16x16x32_bf16 v[18:21], v[182:185], v[208:211], v[18:21]
	v_mfma_f32_16x16x32_bf16 v[6:9], v[174:177], v[216:219], v[6:9]
	v_mfma_f32_16x16x32_bf16 v[2:5], v[182:185], v[216:219], v[2:5]
	s_setprio 0
	s_barrier
	s_add_i32 s63, s63, 2
	s_add_u32 s40, s40, 0x100
	s_addc_u32 s41, s41, 0
	s_add_u32 s61, s61, 0x100
	s_addc_u32 s62, s62, 0
	s_cmp_gt_u32 s63, 13
	s_cbranch_scc0 .LBB0_1034
	v_lshl_add_u32 v150, s6, 8, v1
	v_and_b32_e32 v151, 12, v155
	v_lshlrev_b32_e32 v152, 6, v150
	v_lshl_add_u32 v152, v151, 8, v152
	v_add_u32_e32 v153, 0x2000, v152
	global_load_dwordx4 v[162:165], v152, s[14:15]
	global_load_dwordx4 v[166:169], v152, s[14:15] offset:16
	global_load_dwordx4 v[170:173], v152, s[14:15] offset:32
	global_load_dwordx4 v[174:177], v152, s[14:15] offset:48
	global_load_dwordx4 v[178:181], v153, s[14:15]
	global_load_dwordx4 v[182:185], v153, s[14:15] offset:16
	global_load_dwordx4 v[186:189], v153, s[14:15] offset:32
	global_load_dwordx4 v[190:193], v153, s[14:15] offset:48
	v_lshl_or_b32 v148, s7, 7, v155
	v_lshlrev_b32_e32 v148, 1, v148
	v_mad_u32_u24 v161, v150, s58, v148
	v_mov_b32_e32 v196, 0xbfb8aa3b
	s_and_b64 vcc, exec, s[20:21]
	s_cbranch_vccz .LBB0_1037
	s_barrier
